# attention PV: remaining four scalar O-rescale multiplies packed into two v_pk_mul (on top of packed-softmax version)
# speedup vs baseline: 1.0050x; 1.0011x over previous
; __device__ __forceinline__ unsigned cvt_pk_bf16(float lo, float hi) { unsigned r; asm("v_cvt_pk_bf16_f32 %0, %1, %2" : "=v"(r) : "v"(lo), "v"(hi)); return r; }
; #define LAS __attribute__((address_space(3)))
; #define MFMA16(a, b, c) __builtin_amdgcn_mfma_f32_16x16x32_bf16((a), (b), (c), 0, 0, 0)
; #define ATT_STORE(buf_) do { _Pragma("unroll") for (int i = 0; i < 8; ++i) \
;     *(LAS u32x4*)(st0 + (buf_) * ATT_BUF + ((i >> 2) * 2 + ((i >> 1) & 1)) * ATT_TILE + (i & 1) * 32 * 272) = t[i]; } while (0)
; __device__ __forceinline__ void attn_wg_item(const Params& p, int item, LAS unsigned char* lds) {
;     ...
;     tmax = fmaxf(tmax, __shfl_xor(tmax, 16)); tmax = fmaxf(tmax, __shfl_xor(tmax, 32));
;     const float mnew = fmaxf(mrun, tmax), alpha = __builtin_amdgcn_exp2f(mrun - mnew); mrun = mnew;
;     float psum = 0.f;
; #pragma unroll
;     for (int kt = 0; kt < 4; ++kt)
; #pragma unroll
;       for (int i = 0; i < 4; ++i) { const float e = __builtin_amdgcn_exp2f(S[kt][i] - mnew); S[kt][i] = e; psum += e; }
;     lsum = lsum * alpha + psum;
; #pragma unroll
;     for (int dt = 0; dt < 8; ++dt) O[dt] *= alpha;
;     bf16x8 Pf[2];
; #pragma unroll
;     for (int s2 = 0; s2 < 2; ++s2) { u32x4 wv; wv.x = cvt_pk_bf16(S[2 * s2][0], S[2 * s2][1]); wv.y = cvt_pk_bf16(S[2 * s2][2], S[2 * s2][3]);
;       wv.z = cvt_pk_bf16(S[2 * s2 + 1][0], S[2 * s2 + 1][1]); wv.w = cvt_pk_bf16(S[2 * s2 + 1][2], S[2 * s2 + 1][3]); Pf[s2] = __builtin_bit_cast(bf16x8, wv); }
;     { const int qq = l15 >> 2, pp = l15 & 3; LAS unsigned char* vb = Vl + (4 * kq + qq) * 272 + pp * 8;
; #pragma unroll
;       for (int s2 = 0; s2 < 2; ++s2)
; #pragma unroll
;         for (int dt = 0; dt < 8; ++dt) {
;           const s16x4 lo = __builtin_amdgcn_ds_read_tr16_b64_v4i16((LAS s16x4*)(vb + (32 * s2) * 272 + dt * 32));
;           const s16x4 hi = __builtin_amdgcn_ds_read_tr16_b64_v4i16((LAS s16x4*)(vb + (32 * s2 + 16) * 272 + dt * 32));
;           const bf16x8 Vf = __builtin_shufflevector(lo, hi, 0, 1, 2, 3, 4, 5, 6, 7);
;           O[dt] = MFMA16(Vf, Pf[s2], O[dt]); } }
;     if (ps < 8) ATT_STORE((ps + 1) & 1);
.LBB0_822:
	s_or_b64 exec, exec, s[14:15]
	s_waitcnt lgkmcnt(0)
	s_nop 0
	v_add_f32_e32 v136, v83, v136
	v_max_f32_e32 v80, v158, v158
	v_max_f32_e32 v80, v80, v136
	s_andn2_b64 vcc, exec, s[10:11]
	v_mov_b32_e32 v81, v80
	v_mov_b32_e32 v166, v80
	s_nop 1
	v_permlane16_swap_b32_e32 v81, v166
	v_max_f32_e32 v80, v81, v166
	v_mov_b32_e32 v81, v80
	v_mov_b32_e32 v166, v80
	s_nop 1
	v_permlane32_swap_b32_e32 v81, v166
	v_max3_f32 v81, v155, v81, v166
	v_sub_f32_e32 v80, v155, v81
	v_pk_add_f32 v[82:83], v[122:123], v[80:81] op_sel:[0,1] op_sel_hi:[1,1] neg_lo:[0,1] neg_hi:[0,1]
	v_sub_f32_e32 v123, v136, v81
	v_add3_u32 v136, s16, v139, v140
	v_exp_f32_e32 v80, v80
	v_pk_add_f32 v[88:89], v[128:129], v[80:81] op_sel:[0,1] op_sel_hi:[1,1] neg_lo:[0,1] neg_hi:[0,1]
	v_pk_add_f32 v[90:91], v[130:131], v[80:81] op_sel:[0,1] op_sel_hi:[1,1] neg_lo:[0,1] neg_hi:[0,1]
	v_pk_add_f32 v[92:93], v[132:133], v[80:81] op_sel:[0,1] op_sel_hi:[1,1] neg_lo:[0,1] neg_hi:[0,1]
	v_pk_add_f32 v[94:95], v[134:135], v[80:81] op_sel:[0,1] op_sel_hi:[1,1] neg_lo:[0,1] neg_hi:[0,1]
	ds_read_b64_tr_b16 v[184:185], v136 offset:36864
	ds_read_b64_tr_b16 v[186:187], v136 offset:41472
	ds_read_b64_tr_b16 v[188:189], v136 offset:36896
	ds_read_b64_tr_b16 v[190:191], v136 offset:41504
	ds_read_b64_tr_b16 v[192:193], v136 offset:36928
	ds_read_b64_tr_b16 v[194:195], v136 offset:41536
	ds_read_b64_tr_b16 v[196:197], v136 offset:36960
	ds_read_b64_tr_b16 v[198:199], v136 offset:41568
	ds_read_b64_tr_b16 v[200:201], v136 offset:36992
	ds_read_b64_tr_b16 v[202:203], v136 offset:41600
	ds_read_b64_tr_b16 v[204:205], v136 offset:37024
	ds_read_b64_tr_b16 v[206:207], v136 offset:41632
	ds_read_b64_tr_b16 v[208:209], v136 offset:37056
	ds_read_b64_tr_b16 v[210:211], v136 offset:41664
	v_pk_add_f32 v[84:85], v[124:125], v[80:81] op_sel:[0,1] op_sel_hi:[1,1] neg_lo:[0,1] neg_hi:[0,1]
	v_pk_add_f32 v[86:87], v[126:127], v[80:81] op_sel:[0,1] op_sel_hi:[1,1] neg_lo:[0,1] neg_hi:[0,1]
	v_pk_mul_f32 v[78:79], v[78:79], v[80:81] op_sel_hi:[1,0]
	v_pk_mul_f32 v[76:77], v[76:77], v[80:81] op_sel_hi:[1,0]
	v_pk_mul_f32 v[74:75], v[74:75], v[80:81] op_sel_hi:[1,0]
	v_pk_mul_f32 v[72:73], v[72:73], v[80:81] op_sel_hi:[1,0]
	v_pk_mul_f32 v[70:71], v[70:71], v[80:81] op_sel_hi:[1,0]
	v_pk_mul_f32 v[68:69], v[68:69], v[80:81] op_sel_hi:[1,0]
	v_pk_mul_f32 v[66:67], v[66:67], v[80:81] op_sel_hi:[1,0]
	v_pk_mul_f32 v[64:65], v[64:65], v[80:81] op_sel_hi:[1,0]
	v_exp_f32_e32 v82, v82
	v_exp_f32_e32 v83, v83
	v_exp_f32_e32 v84, v84
	v_exp_f32_e32 v85, v85
	v_exp_f32_e32 v86, v86
	v_exp_f32_e32 v87, v87
	v_exp_f32_e32 v88, v88
	v_exp_f32_e32 v89, v89
	v_cvt_pk_bf16_f32 v124, v82, v83
	v_cvt_pk_bf16_f32 v125, v84, v85
	v_cvt_pk_bf16_f32 v126, v86, v87
	v_cvt_pk_bf16_f32 v127, v88, v89
	v_pk_mul_f32 v[62:63], v[62:63], v[80:81] op_sel_hi:[1,0]
	s_waitcnt lgkmcnt(12)
	v_mfma_f32_16x16x32_bf16 v[76:79], v[184:187], v[124:127], v[76:79]
	ds_read_b64_tr_b16 v[212:213], v136 offset:37088
	ds_read_b64_tr_b16 v[214:215], v136 offset:41696
	v_pk_mul_f32 v[60:61], v[60:61], v[80:81] op_sel_hi:[1,0]
	v_pk_mul_f32 v[58:59], v[58:59], v[80:81] op_sel_hi:[1,0]
	s_waitcnt lgkmcnt(12)
	v_mfma_f32_16x16x32_bf16 v[72:75], v[188:191], v[124:127], v[72:75]
	ds_read_b64_tr_b16 v[216:217], v136 offset:46080
	ds_read_b64_tr_b16 v[218:219], v136 offset:50688
	v_pk_mul_f32 v[56:57], v[56:57], v[80:81] op_sel_hi:[1,0]
	v_pk_mul_f32 v[38:39], v[38:39], v[80:81] op_sel_hi:[1,0]
	v_pk_mul_f32 v[36:37], v[36:37], v[80:81] op_sel_hi:[1,0]
	s_waitcnt lgkmcnt(12)
	v_mfma_f32_16x16x32_bf16 v[68:71], v[192:195], v[124:127], v[68:71]
	ds_read_b64_tr_b16 v[220:221], v136 offset:46112
	ds_read_b64_tr_b16 v[222:223], v136 offset:50720
	v_pk_mul_f32 v[30:31], v[30:31], v[80:81] op_sel_hi:[1,0]
	v_pk_mul_f32 v[28:29], v[28:29], v[80:81] op_sel_hi:[1,0]
	v_sub_f32_e32 v122, v157, v81
	s_waitcnt lgkmcnt(12)
	v_mfma_f32_16x16x32_bf16 v[64:67], v[196:199], v[124:127], v[64:67]
	ds_read_b64_tr_b16 v[224:225], v136 offset:46144
	ds_read_b64_tr_b16 v[226:227], v136 offset:50752
	v_exp_f32_e32 v90, v90
	v_exp_f32_e32 v91, v91
	s_waitcnt lgkmcnt(12)
	v_mfma_f32_16x16x32_bf16 v[60:63], v[200:203], v[124:127], v[60:63]
	ds_read_b64_tr_b16 v[228:229], v136 offset:46176
	ds_read_b64_tr_b16 v[230:231], v136 offset:50784
	v_exp_f32_e32 v92, v92
	v_exp_f32_e32 v93, v93
	v_exp_f32_e32 v94, v94
	s_waitcnt lgkmcnt(12)
	v_mfma_f32_16x16x32_bf16 v[56:59], v[204:207], v[124:127], v[56:59]
	ds_read_b64_tr_b16 v[232:233], v136 offset:46208
	ds_read_b64_tr_b16 v[234:235], v136 offset:50816
	v_exp_f32_e32 v95, v95
	v_exp_f32_e32 v122, v122
	s_waitcnt lgkmcnt(12)
	v_mfma_f32_16x16x32_bf16 v[36:39], v[208:211], v[124:127], v[36:39]
	ds_read_b64_tr_b16 v[236:237], v136 offset:46240
	ds_read_b64_tr_b16 v[238:239], v136 offset:50848
	v_exp_f32_e32 v123, v123
	v_cvt_pk_bf16_f32 v128, v90, v91
	v_cvt_pk_bf16_f32 v129, v92, v93
	s_waitcnt lgkmcnt(12)
	v_mfma_f32_16x16x32_bf16 v[28:31], v[212:215], v[124:127], v[28:31]
	ds_read_b64_tr_b16 v[240:241], v136 offset:46272
	ds_read_b64_tr_b16 v[242:243], v136 offset:50880
	v_cvt_pk_bf16_f32 v130, v94, v95
	v_cvt_pk_bf16_f32 v131, v122, v123
	s_nop 1
	s_waitcnt lgkmcnt(12)
	v_mfma_f32_16x16x32_bf16 v[76:79], v[216:219], v[128:131], v[76:79]
	ds_read_b64_tr_b16 v[172:173], v136 offset:46304
	ds_read_b64_tr_b16 v[174:175], v136 offset:50912
	s_waitcnt lgkmcnt(12)
	v_mfma_f32_16x16x32_bf16 v[72:75], v[220:223], v[128:131], v[72:75]
	s_waitcnt lgkmcnt(10)
	v_mfma_f32_16x16x32_bf16 v[68:71], v[224:227], v[128:131], v[68:71]
	s_waitcnt lgkmcnt(8)
	v_mfma_f32_16x16x32_bf16 v[64:67], v[228:231], v[128:131], v[64:67]
	s_waitcnt lgkmcnt(6)
	v_mfma_f32_16x16x32_bf16 v[60:63], v[232:235], v[128:131], v[60:63]
	s_waitcnt lgkmcnt(4)
	v_mfma_f32_16x16x32_bf16 v[56:59], v[236:239], v[128:131], v[56:59]
	s_waitcnt lgkmcnt(2)
	v_mfma_f32_16x16x32_bf16 v[36:39], v[240:243], v[128:131], v[36:39]
	s_waitcnt lgkmcnt(0)
	v_mfma_f32_16x16x32_bf16 v[28:31], v[172:175], v[128:131], v[28:31]
	s_cbranch_vccnz .LBB0_824
	s_andn2_b32 s10, 1, s8
	s_mul_i32 s10, s10, 0x12000
	v_add_u32_e32 v124, s10, v137
	s_waitcnt vmcnt(0)
	ds_write_b128 v124, v[0:3]
	ds_write_b128 v124, v[8:11] offset:9216
	ds_write_b128 v124, v[4:7] offset:18432
	ds_write_b128 v124, v[16:19] offset:27648
	ds_write_b128 v124, v[12:15] offset:36864
	ds_write_b128 v124, v[24:27] offset:46080
	ds_write_b128 v124, v[20:23] offset:55296
	ds_write_b128 v124, v[32:35] offset:64512
